# v9
# speedup vs baseline: 1.0373x; 1.0044x over previous
; #define ATT_QK(S0_, S1_, kf_) do { \
;     _Pragma("unroll") for (int i_ = 0; i_ < 16; ++i_) { S0_[i_] = 0.f; S1_[i_] = 0.f; } \
;     _Pragma("unroll") for (int kk_ = 0; kk_ < 4; ++kk_) { \
;       S0_ = __builtin_amdgcn_mfma_f32_32x32x16_bf16(kf_[kk_], qf[0][kk_], S0_, 0, 0, 0); \
;       S1_ = __builtin_amdgcn_mfma_f32_32x32x16_bf16(kf_[kk_], qf[1][kk_], S1_, 0, 0, 0); } } while (0)
; #define ATT_PV(vf_, P0_, P1_) do { \
;     _Pragma("unroll") for (int c_ = 0; c_ < 2; ++c_) \
;     _Pragma("unroll") for (int db_ = 0; db_ < 2; ++db_) { \
;       O[db_][0] = __builtin_amdgcn_mfma_f32_32x32x16_bf16(vf_[db_ * 2 + c_], P0_[c_], O[db_][0], 0, 0, 0); \
;       O[db_][1] = __builtin_amdgcn_mfma_f32_32x32x16_bf16(vf_[db_ * 2 + c_], P1_[c_], O[db_][1], 0, 0, 0); } } while (0)
; __device__ __forceinline__ void exp_pack(f32x16& s, float& l, bf16x8& p0, bf16x8& p1) {
; #pragma unroll
;   for (int i = 0; i < 16; ++i) s[i] = __builtin_amdgcn_exp2f(s[i]);
;   const float a0 = (s[0] + s[1]) + (s[2] + s[3]), a1 = (s[4] + s[5]) + (s[6] + s[7]);
;   const float a2 = (s[8] + s[9]) + (s[10] + s[11]), a3 = (s[12] + s[13]) + (s[14] + s[15]);
;   l += (a0 + a1) + (a2 + a3);
;   p0 = pack8(s, 0); p1 = pack8(s, 8);
; }
; __device__ __forceinline__ void attn_item_fast(const u16* __restrict__ Qg, const u16* __restrict__ Kg, const u16* __restrict__ Vtg,
;                                                u16* __restrict__ Og, const int L, char* smem, const int tid) {
;     ...
;   for (int t = 0; t < NT; ++t) {
;     const int cur = (t & 1) * 8192;
;     const char* Kb = Ks + cur; const char* Vb = Vs + cur;
;     if (t + 1 < NT) {
;       const char* kb_ = (const char*)Kg + (size_t)(t + 1) * (64 * 256 * 2);
;       const char* vb_ = (const char*)Vtg + (size_t)(t + 1) * 128;
;       glds16(koff, kb_, ldsK + (unsigned)(cur ^ 8192)); glds16(voff, vb_, ldsV + (unsigned)(cur ^ 8192));
;     }
;     ld_kf<0>(kf, Kb, r32, hi, sw);
;     ATT_PV(vf, P0, P1);
;     ld_vf<0>(vf, Vb, r32, hi, sw);
;     ATT_QK(S0, S1, kf);
;     ld_kf<1>(kf, Kb, r32, hi, sw);
;     WBAR();
;     exp_pack(S0, l0, P0[0], P0[1]); exp_pack(S1, l1, P1[0], P1[1]);
;     WBAR();
;     ATT_PV(vf, P0, P1);
;     ld_vf<1>(vf, Vb, r32, hi, sw);
;     ATT_QK(S0, S1, kf);
;     asm volatile("s_waitcnt vmcnt(0) lgkmcnt(0)" ::: "memory");
;     WBAR();
;     exp_pack(S0, l0, P0[0], P0[1]); exp_pack(S1, l1, P1[0], P1[1]);
;     WBAR();
.LBB0_93:
	s_and_b32 s3, s53, 0x2000
	s_xor_b32 s13, s3, 0x2000
	s_add_i32 s15, s13, s49
	s_add_i32 s13, s13, s48
	s_mov_b32 s52, m0
	s_mov_b32 m0, s13
	s_nop 0
	global_load_lds_dwordx4 v179, s[34:35]
	s_mov_b32 m0, s52
	v_add_u32_e32 v82, s3, v181
	s_mov_b32 s13, m0
	s_mov_b32 m0, s15
	s_nop 0
	global_load_lds_dwordx4 v180, s[38:39]
	s_mov_b32 m0, s13
	v_add_u32_e32 v188, v82, v182
	ds_read_b128 v[146:149], v188
	s_waitcnt lgkmcnt(4)
	v_mfma_f32_32x32x16_bf16 v[50:65], v[142:145], v[74:77], v[50:65]
	v_add_u32_e32 v189, v82, v183
	ds_read_b128 v[150:153], v189
	v_add_u32_e32 v186, v82, v184
	v_add_u32_e32 v187, v82, v185
	ds_read_b128 v[154:157], v186
	ds_read_b128 v[158:161], v187
	v_mfma_f32_32x32x16_bf16 v[18:33], v[142:145], v[78:81], v[18:33]
	s_waitcnt lgkmcnt(6)
	v_mfma_f32_32x32x16_bf16 v[34:49], v[138:141], v[74:77], v[34:49]
	v_mfma_f32_32x32x16_bf16 v[2:17], v[138:141], v[78:81], v[2:17]
	s_waitcnt lgkmcnt(5)
	v_mfma_f32_32x32x16_bf16 v[50:65], v[134:137], v[70:73], v[50:65]
	v_mfma_f32_32x32x16_bf16 v[18:33], v[134:137], v[66:69], v[18:33]
	s_waitcnt lgkmcnt(4)
	v_mfma_f32_32x32x16_bf16 v[34:49], v[130:133], v[70:73], v[34:49]
	v_mfma_f32_32x32x16_bf16 v[2:17], v[130:133], v[66:69], v[2:17]
	ds_read_b128 v[142:145], v188 offset:16384
	ds_read_b128 v[134:137], v189 offset:16384
	ds_read_b128 v[138:141], v188 offset:20480
	ds_read_b128 v[130:133], v189 offset:20480
	s_waitcnt lgkmcnt(7)
	v_mfma_f32_32x32x16_bf16 v[66:81], v[146:149], v[126:129], 0
	v_mfma_f32_32x32x16_bf16 v[82:97], v[146:149], v[118:121], 0
	s_waitcnt lgkmcnt(6)
	v_mfma_f32_32x32x16_bf16 v[66:81], v[150:153], v[122:125], v[66:81]
	v_mfma_f32_32x32x16_bf16 v[82:97], v[150:153], v[114:117], v[82:97]
	s_waitcnt lgkmcnt(5)
	v_mfma_f32_32x32x16_bf16 v[66:81], v[154:157], v[110:113], v[66:81]
	v_mfma_f32_32x32x16_bf16 v[82:97], v[154:157], v[106:109], v[82:97]
	s_waitcnt lgkmcnt(4)
	v_mfma_f32_32x32x16_bf16 v[66:81], v[158:161], v[98:101], v[66:81]
	v_mfma_f32_32x32x16_bf16 v[82:97], v[158:161], v[102:105], v[82:97]
	ds_read_b128 v[146:149], v188 offset:4096
	ds_read_b128 v[150:153], v189 offset:4096
	ds_read_b128 v[154:157], v186 offset:4096
	ds_read_b128 v[158:161], v187 offset:4096
	s_barrier
	s_setprio 0
	s_nop 6
	v_exp_f32_e32 v82, v82
	v_exp_f32_e32 v188, v83
	v_exp_f32_e32 v84, v84
	v_exp_f32_e32 v206, v85
	v_exp_f32_e32 v83, v66
	v_exp_f32_e32 v189, v67
	v_exp_f32_e32 v85, v68
	v_exp_f32_e32 v207, v69
	v_exp_f32_e32 v86, v86
	v_exp_f32_e32 v208, v87
	v_exp_f32_e32 v88, v88
	v_exp_f32_e32 v210, v89
	v_exp_f32_e32 v87, v70
	v_exp_f32_e32 v209, v71
	v_exp_f32_e32 v89, v72
	v_exp_f32_e32 v211, v73
	v_exp_f32_e32 v90, v90
	v_exp_f32_e32 v212, v91
	v_exp_f32_e32 v92, v92
	v_exp_f32_e32 v214, v93
	v_exp_f32_e32 v91, v74
	v_exp_f32_e32 v213, v75
	v_exp_f32_e32 v93, v76
	v_exp_f32_e32 v215, v77
	v_exp_f32_e32 v94, v94
	v_exp_f32_e32 v216, v95
	v_exp_f32_e32 v96, v96
	v_exp_f32_e32 v218, v97
	v_exp_f32_e32 v95, v78
	v_exp_f32_e32 v217, v79
	v_exp_f32_e32 v97, v80
	v_exp_f32_e32 v219, v81
	v_add_f32_e32 v74, v82, v188
	v_add_f32_e32 v75, v83, v189
	v_add_f32_e32 v76, v84, v206
	v_add_f32_e32 v77, v85, v207
	v_add_f32_e32 v78, v88, v210
	v_add_f32_e32 v79, v89, v211
	v_add_f32_e32 v74, v74, v76
	v_add_f32_e32 v75, v75, v77
	v_add_f32_e32 v76, v86, v208
	v_add_f32_e32 v77, v87, v209
	v_add_f32_e32 v80, v92, v214
	v_add_f32_e32 v81, v93, v215
	v_add_f32_e32 v76, v76, v78
	v_add_f32_e32 v77, v77, v79
	v_add_f32_e32 v78, v90, v212
	v_add_f32_e32 v79, v91, v213
	v_add_f32_e32 v220, v96, v218
	v_add_f32_e32 v221, v97, v219
	v_add_f32_e32 v78, v78, v80
	v_add_f32_e32 v79, v79, v81
	v_add_f32_e32 v80, v94, v216
	v_add_f32_e32 v81, v95, v217
	v_add_f32_e32 v74, v74, v76
	v_add_f32_e32 v75, v75, v77
	v_add_f32_e32 v80, v80, v220
	v_add_f32_e32 v81, v81, v221
	v_cvt_pk_bf16_f32 v66, v82, v188
	v_cvt_pk_bf16_f32 v67, v84, v206
	v_cvt_pk_bf16_f32 v68, v86, v208
	v_cvt_pk_bf16_f32 v69, v88, v210
	v_cvt_pk_bf16_f32 v70, v90, v212
	s_nop 0
	v_add_f32_e32 v76, v78, v80
	v_add_f32_e32 v77, v79, v81
	v_cvt_pk_bf16_f32 v71, v92, v214
	v_cvt_pk_bf16_f32 v72, v94, v216
	v_cvt_pk_bf16_f32 v73, v96, v218
	v_cvt_pk_bf16_f32 v78, v91, v213
	v_cvt_pk_bf16_f32 v79, v93, v215
	s_nop 0
	v_add_f32_e32 v220, v74, v76
	v_add_f32_e32 v221, v75, v77
	v_cvt_pk_bf16_f32 v74, v83, v189
	v_cvt_pk_bf16_f32 v75, v85, v207
	v_cvt_pk_bf16_f32 v76, v87, v209
	v_cvt_pk_bf16_f32 v77, v89, v211
	v_cvt_pk_bf16_f32 v80, v95, v217
	v_cvt_pk_bf16_f32 v81, v97, v219
	s_barrier
	s_setprio 1
	s_waitcnt lgkmcnt(7)
	v_mfma_f32_32x32x16_bf16 v[50:65], v[142:145], v[66:69], v[50:65]
	v_mfma_f32_32x32x16_bf16 v[18:33], v[142:145], v[74:77], v[18:33]
	s_waitcnt lgkmcnt(5)
	v_mfma_f32_32x32x16_bf16 v[34:49], v[138:141], v[66:69], v[34:49]
	v_mfma_f32_32x32x16_bf16 v[2:17], v[138:141], v[74:77], v[2:17]
	v_mfma_f32_32x32x16_bf16 v[50:65], v[134:137], v[70:73], v[50:65]
	v_mfma_f32_32x32x16_bf16 v[18:33], v[134:137], v[78:81], v[18:33]
	s_waitcnt lgkmcnt(4)
	v_mfma_f32_32x32x16_bf16 v[34:49], v[130:133], v[70:73], v[34:49]
	v_mfma_f32_32x32x16_bf16 v[2:17], v[130:133], v[78:81], v[2:17]
	ds_read_b128 v[142:145], v186 offset:16384
	ds_read_b128 v[138:141], v186 offset:20480
	ds_read_b128 v[134:137], v187 offset:16384
	ds_read_b128 v[130:133], v187 offset:20480
	s_waitcnt vmcnt(0) lgkmcnt(0)
	s_waitcnt lgkmcnt(7)
	v_mfma_f32_32x32x16_bf16 v[66:81], v[146:149], v[126:129], 0
	v_mfma_f32_32x32x16_bf16 v[82:97], v[146:149], v[118:121], 0
	v_add_f32_e64 v146, v172, v220
	v_add_f32_e64 v147, v173, v221
	s_waitcnt lgkmcnt(6)
	v_mfma_f32_32x32x16_bf16 v[66:81], v[150:153], v[122:125], v[66:81]
	v_mfma_f32_32x32x16_bf16 v[82:97], v[150:153], v[114:117], v[82:97]
	s_waitcnt lgkmcnt(5)
	v_mfma_f32_32x32x16_bf16 v[66:81], v[154:157], v[110:113], v[66:81]
	v_mfma_f32_32x32x16_bf16 v[82:97], v[154:157], v[106:109], v[82:97]
	s_waitcnt lgkmcnt(4)
	v_mfma_f32_32x32x16_bf16 v[66:81], v[158:161], v[98:101], v[66:81]
	v_mfma_f32_32x32x16_bf16 v[82:97], v[158:161], v[102:105], v[82:97]
	s_barrier
; #define ATT_QK(S0_, S1_, kf_) do { \
;     _Pragma("unroll") for (int i_ = 0; i_ < 16; ++i_) { S0_[i_] = 0.f; S1_[i_] = 0.f; } \
;     _Pragma("unroll") for (int kk_ = 0; kk_ < 4; ++kk_) { \
;       S0_ = __builtin_amdgcn_mfma_f32_32x32x16_bf16(kf_[kk_], qf[0][kk_], S0_, 0, 0, 0); \
;       S1_ = __builtin_amdgcn_mfma_f32_32x32x16_bf16(kf_[kk_], qf[1][kk_], S1_, 0, 0, 0); } } while (0)
; #define ATT_PV(vf_, P0_, P1_) do { \
;     _Pragma("unroll") for (int c_ = 0; c_ < 2; ++c_) \
;     _Pragma("unroll") for (int db_ = 0; db_ < 2; ++db_) { \
;       O[db_][0] = __builtin_amdgcn_mfma_f32_32x32x16_bf16(vf_[db_ * 2 + c_], P0_[c_], O[db_][0], 0, 0, 0); \
;       O[db_][1] = __builtin_amdgcn_mfma_f32_32x32x16_bf16(vf_[db_ * 2 + c_], P1_[c_], O[db_][1], 0, 0, 0); } } while (0)
; #define WBAR() do { __builtin_amdgcn_sched_barrier(0); __builtin_amdgcn_s_barrier(); __builtin_amdgcn_sched_barrier(0); } while (0)
; __device__ __forceinline__ void attn_item_fast(const u16* __restrict__ Qg, const u16* __restrict__ Kg, const u16* __restrict__ Vtg,
;                                                u16* __restrict__ Og, const int L, char* smem, const int tid) {
;     ...
;     exp_pack(S0, l0, P0[0], P0[1]); exp_pack(S1, l1, P1[0], P1[1]);
;     WBAR();
;     ATT_PV(vf, P0, P1);
;     ld_vf<1>(vf, Vb, r32, hi, sw);
;     ATT_QK(S0, S1, kf);
;     asm volatile("s_waitcnt vmcnt(0) lgkmcnt(0)" ::: "memory");
;     WBAR();
;     exp_pack(S0, l0, P0[0], P0[1]); exp_pack(S1, l1, P1[0], P1[1]);
;     WBAR();
;   }
;   if (half == 0) WBAR();
	s_setprio 0
	s_nop 10
	v_exp_f32_e32 v82, v82
	v_exp_f32_e32 v148, v83
	v_exp_f32_e32 v84, v84
	v_exp_f32_e32 v150, v85
	v_exp_f32_e32 v83, v66
	v_exp_f32_e32 v149, v67
	v_exp_f32_e32 v85, v68
	v_exp_f32_e32 v151, v69
	v_exp_f32_e32 v86, v86
	v_exp_f32_e32 v152, v87
	v_exp_f32_e32 v88, v88
	v_exp_f32_e32 v154, v89
	v_exp_f32_e32 v87, v70
	v_exp_f32_e32 v153, v71
	v_exp_f32_e32 v89, v72
	v_exp_f32_e32 v155, v73
	v_exp_f32_e32 v90, v90
	v_exp_f32_e32 v156, v91
	v_exp_f32_e32 v92, v92
	v_exp_f32_e32 v158, v93
	v_exp_f32_e32 v91, v74
	v_exp_f32_e32 v157, v75
	v_exp_f32_e32 v93, v76
	v_exp_f32_e32 v159, v77
	v_exp_f32_e32 v94, v94
	v_exp_f32_e32 v160, v95
	v_exp_f32_e32 v96, v96
	v_exp_f32_e32 v186, v97
	v_exp_f32_e32 v95, v78
	v_exp_f32_e32 v161, v79
	v_exp_f32_e32 v97, v80
	v_exp_f32_e32 v187, v81
	v_add_f32_e32 v66, v82, v148
	v_add_f32_e32 v67, v83, v149
	v_add_f32_e32 v68, v84, v150
	v_add_f32_e32 v69, v85, v151
	v_add_f32_e32 v70, v88, v154
	v_add_f32_e32 v71, v89, v155
	v_add_f32_e32 v66, v66, v68
	v_add_f32_e32 v67, v67, v69
	v_add_f32_e32 v68, v86, v152
	v_add_f32_e32 v69, v87, v153
	v_add_f32_e32 v72, v92, v158
	v_add_f32_e32 v73, v93, v159
	v_add_f32_e32 v68, v68, v70
	v_add_f32_e32 v69, v69, v71
	v_add_f32_e32 v70, v90, v156
	v_add_f32_e32 v71, v91, v157
	v_add_f32_e32 v74, v96, v186
	v_add_f32_e32 v75, v97, v187
	v_add_f32_e32 v70, v70, v72
	v_add_f32_e32 v71, v71, v73
	v_add_f32_e32 v72, v94, v160
	v_add_f32_e32 v73, v95, v161
	v_add_f32_e32 v66, v66, v68
	v_add_f32_e32 v67, v67, v69
	v_add_f32_e32 v72, v72, v74
	v_add_f32_e32 v73, v73, v75
	v_cvt_pk_bf16_f32 v74, v82, v148
	v_cvt_pk_bf16_f32 v75, v84, v150
	v_cvt_pk_bf16_f32 v76, v86, v152
	v_cvt_pk_bf16_f32 v77, v88, v154
	v_cvt_pk_bf16_f32 v78, v83, v149
	s_nop 0
	v_add_f32_e32 v68, v70, v72
	v_add_f32_e32 v69, v71, v73
	v_cvt_pk_bf16_f32 v70, v90, v156
	v_cvt_pk_bf16_f32 v71, v92, v158
	v_cvt_pk_bf16_f32 v72, v94, v160
	v_cvt_pk_bf16_f32 v73, v96, v186
	v_cvt_pk_bf16_f32 v79, v85, v151
	s_nop 0
	v_add_f32_e32 v66, v66, v68
	v_add_f32_e32 v67, v67, v69
	v_cvt_pk_bf16_f32 v80, v87, v153
	v_cvt_pk_bf16_f32 v81, v89, v155
	v_cvt_pk_bf16_f32 v68, v95, v161
	v_cvt_pk_bf16_f32 v69, v97, v187
	s_nop 0
	v_add_f32_e32 v172, v146, v66
	v_add_f32_e32 v173, v147, v67
	v_cvt_pk_bf16_f32 v66, v91, v157
	v_cvt_pk_bf16_f32 v67, v93, v159
	s_barrier
	s_setprio 1
	s_addk_i32 s53, 0x2000
	s_add_u32 s34, s34, 0x8000
	s_addc_u32 s35, s35, 0
	s_add_u32 s38, s38, 0x80
	s_addc_u32 s39, s39, 0
	s_cmp_eq_u32 s53, 0x1fe000
	s_cbranch_scc0 .LBB0_93
	s_setprio 0
	v_add_u32_e32 v205, v181, v182
	ds_read_b128 v[146:149], v205 offset:8192
	s_waitcnt lgkmcnt(4)
	v_mfma_f32_32x32x16_bf16 v[50:65], v[142:145], v[74:77], v[50:65]
	v_add_u32_e32 v222, v181, v183
	ds_read_b128 v[150:153], v222 offset:8192
	v_add_u32_e32 v234, v181, v184
	ds_read_b128 v[154:157], v234 offset:8192
	v_add_u32_e32 v235, v181, v185
	ds_read_b128 v[158:161], v235 offset:8192
	ds_read_b128 v[186:189], v205 offset:24576
	ds_read_b128 v[206:209], v222 offset:24576
	ds_read_b128 v[210:213], v205 offset:28672
	ds_read_b128 v[214:217], v222 offset:28672
	v_mfma_f32_32x32x16_bf16 v[18:33], v[142:145], v[78:81], v[18:33]
	ds_read_b128 v[218:221], v205 offset:12288
	ds_read_b128 v[222:225], v222 offset:12288
	ds_read_b128 v[226:229], v234 offset:12288
	ds_read_b128 v[230:233], v235 offset:12288
	s_waitcnt lgkmcnt(14)
	v_mfma_f32_32x32x16_bf16 v[34:49], v[138:141], v[74:77], v[34:49]
	v_mfma_f32_32x32x16_bf16 v[2:17], v[138:141], v[78:81], v[2:17]
	s_waitcnt lgkmcnt(13)
	v_mfma_f32_32x32x16_bf16 v[50:65], v[134:137], v[70:73], v[50:65]
	v_mfma_f32_32x32x16_bf16 v[18:33], v[134:137], v[66:69], v[18:33]
	s_waitcnt lgkmcnt(12)
	v_mfma_f32_32x32x16_bf16 v[34:49], v[130:133], v[70:73], v[34:49]
	v_mfma_f32_32x32x16_bf16 v[2:17], v[130:133], v[66:69], v[2:17]
	s_waitcnt lgkmcnt(11)
	v_mfma_f32_32x32x16_bf16 v[82:97], v[146:149], v[118:121], 0
	v_mfma_f32_32x32x16_bf16 v[66:81], v[146:149], v[126:129], 0
	s_waitcnt lgkmcnt(10)
	v_mfma_f32_32x32x16_bf16 v[82:97], v[150:153], v[114:117], v[82:97]
	v_mfma_f32_32x32x16_bf16 v[66:81], v[150:153], v[122:125], v[66:81]
	s_waitcnt lgkmcnt(9)
	v_mfma_f32_32x32x16_bf16 v[82:97], v[154:157], v[106:109], v[82:97]
	v_mfma_f32_32x32x16_bf16 v[66:81], v[154:157], v[110:113], v[66:81]
	s_waitcnt lgkmcnt(8)
	v_mfma_f32_32x32x16_bf16 v[82:97], v[158:161], v[102:105], v[82:97]
	v_mfma_f32_32x32x16_bf16 v[66:81], v[158:161], v[98:101], v[66:81]
	s_barrier
; #define ATT_QK(S0_, S1_, kf_) do { \
;     _Pragma("unroll") for (int i_ = 0; i_ < 16; ++i_) { S0_[i_] = 0.f; S1_[i_] = 0.f; } \
;     _Pragma("unroll") for (int kk_ = 0; kk_ < 4; ++kk_) { \
;       S0_ = __builtin_amdgcn_mfma_f32_32x32x16_bf16(kf_[kk_], qf[0][kk_], S0_, 0, 0, 0); \
;       S1_ = __builtin_amdgcn_mfma_f32_32x32x16_bf16(kf_[kk_], qf[1][kk_], S1_, 0, 0, 0); } } while (0)
; #define ATT_PV(vf_, P0_, P1_) do { \
;     _Pragma("unroll") for (int c_ = 0; c_ < 2; ++c_) \
;     _Pragma("unroll") for (int db_ = 0; db_ < 2; ++db_) { \
;       O[db_][0] = __builtin_amdgcn_mfma_f32_32x32x16_bf16(vf_[db_ * 2 + c_], P0_[c_], O[db_][0], 0, 0, 0); \
;       O[db_][1] = __builtin_amdgcn_mfma_f32_32x32x16_bf16(vf_[db_ * 2 + c_], P1_[c_], O[db_][1], 0, 0, 0); } } while (0)
; #define WBAR() do { __builtin_amdgcn_sched_barrier(0); __builtin_amdgcn_s_barrier(); __builtin_amdgcn_sched_barrier(0); } while (0)
; __device__ __forceinline__ void attn_item_fast(const u16* __restrict__ Qg, const u16* __restrict__ Kg, const u16* __restrict__ Vtg,
;                                                u16* __restrict__ Og, const int L, char* smem, const int tid) {
;     ...
;     ld_kf<0>(kf, Kb, r32, hi, sw);
;     ATT_PV(vf, P0, P1);
;     ld_vf<0>(vf, Vb, r32, hi, sw);
;     ATT_QK(S0, S1, kf);
;     ld_kf<1>(kf, Kb, r32, hi, sw);
;     WBAR();
;     exp_pack(S0, l0, P0[0], P0[1]); exp_pack(S1, l1, P1[0], P1[1]);
;     WBAR();
;     ATT_PV(vf, P0, P1);
;     ld_vf<1>(vf, Vb, r32, hi, sw);
;     ATT_QK(S0, S1, kf);
;     asm volatile("s_waitcnt vmcnt(0) lgkmcnt(0)" ::: "memory");
;     WBAR();
;     exp_pack(S0, l0, P0[0], P0[1]); exp_pack(S1, l1, P1[0], P1[1]);
;     WBAR();
;   }
;   if (half == 0) WBAR();
	s_nop 9
	v_exp_f32_e32 v138, v82
	v_exp_f32_e32 v144, v83
	v_exp_f32_e32 v132, v84
	v_exp_f32_e32 v139, v85
	v_exp_f32_e32 v133, v86
	v_exp_f32_e32 v140, v87
	v_exp_f32_e32 v141, v88
	v_exp_f32_e32 v145, v89
	v_exp_f32_e32 v134, v90
	v_exp_f32_e32 v142, v91
	v_exp_f32_e32 v130, v92
	v_exp_f32_e32 v135, v93
	v_exp_f32_e32 v131, v94
	v_exp_f32_e32 v136, v95
	v_exp_f32_e32 v137, v96
	v_exp_f32_e32 v143, v97
	v_exp_f32_e32 v146, v66
	v_exp_f32_e32 v147, v67
	v_exp_f32_e32 v148, v68
	v_exp_f32_e32 v151, v69
	v_exp_f32_e32 v149, v70
	v_exp_f32_e32 v152, v71
	v_exp_f32_e32 v153, v72
	v_exp_f32_e32 v157, v73
	v_exp_f32_e32 v150, v74
	v_exp_f32_e32 v154, v75
	v_exp_f32_e32 v155, v76
	v_exp_f32_e32 v158, v77
	v_exp_f32_e32 v156, v78
	v_exp_f32_e32 v159, v79
	v_exp_f32_e32 v160, v80
	v_exp_f32_e32 v161, v81
	v_cvt_pk_bf16_f32 v82, v138, v144
	v_cvt_pk_bf16_f32 v83, v132, v139
	v_cvt_pk_bf16_f32 v84, v133, v140
	v_cvt_pk_bf16_f32 v85, v141, v145
	v_cvt_pk_bf16_f32 v86, v134, v142
	v_cvt_pk_bf16_f32 v87, v130, v135
	v_cvt_pk_bf16_f32 v88, v131, v136
	v_cvt_pk_bf16_f32 v89, v137, v143
	v_cvt_pk_bf16_f32 v66, v146, v147
	v_cvt_pk_bf16_f32 v67, v148, v151
	v_cvt_pk_bf16_f32 v68, v149, v152
	v_cvt_pk_bf16_f32 v69, v153, v157
	v_cvt_pk_bf16_f32 v70, v150, v154
	v_cvt_pk_bf16_f32 v71, v155, v158
	v_cvt_pk_bf16_f32 v72, v156, v159
	v_cvt_pk_bf16_f32 v73, v160, v161
	s_barrier
	s_waitcnt lgkmcnt(7)
	v_mfma_f32_32x32x16_bf16 v[50:65], v[186:189], v[82:85], v[50:65]
	v_mfma_f32_32x32x16_bf16 v[18:33], v[186:189], v[66:69], v[18:33]
	s_waitcnt lgkmcnt(5)
	v_mfma_f32_32x32x16_bf16 v[34:49], v[210:213], v[82:85], v[34:49]
	v_mfma_f32_32x32x16_bf16 v[2:17], v[210:213], v[66:69], v[2:17]
	v_mfma_f32_32x32x16_bf16 v[50:65], v[206:209], v[86:89], v[50:65]
	v_mfma_f32_32x32x16_bf16 v[18:33], v[206:209], v[70:73], v[18:33]
	s_waitcnt lgkmcnt(4)
	v_mfma_f32_32x32x16_bf16 v[34:49], v[214:217], v[86:89], v[34:49]
	v_mfma_f32_32x32x16_bf16 v[2:17], v[214:217], v[70:73], v[2:17]
	s_waitcnt lgkmcnt(3)
	v_mfma_f32_32x32x16_bf16 v[82:97], v[218:221], v[118:121], 0
	v_mfma_f32_32x32x16_bf16 v[66:81], v[218:221], v[126:129], 0
	s_waitcnt lgkmcnt(2)
	v_mfma_f32_32x32x16_bf16 v[82:97], v[222:225], v[114:117], v[82:97]
	v_mfma_f32_32x32x16_bf16 v[66:81], v[222:225], v[122:125], v[66:81]
	s_waitcnt lgkmcnt(1)
	v_mfma_f32_32x32x16_bf16 v[82:97], v[226:229], v[106:109], v[82:97]
	v_mfma_f32_32x32x16_bf16 v[66:81], v[226:229], v[110:113], v[66:81]
	s_waitcnt lgkmcnt(0)
	v_mfma_f32_32x32x16_bf16 v[82:97], v[230:233], v[102:105], v[82:97]
	ds_read_b128 v[114:117], v234 offset:24576
	ds_read_b128 v[110:113], v234 offset:28672
	ds_read_b128 v[106:109], v235 offset:24576
	ds_read_b128 v[102:105], v235 offset:28672
	s_waitcnt vmcnt(0) lgkmcnt(0)
	v_mfma_f32_32x32x16_bf16 v[66:81], v[230:233], v[98:101], v[66:81]
	s_barrier
	s_nop 5
	v_exp_f32_e32 v98, v82
	v_exp_f32_e32 v99, v83
	v_exp_f32_e32 v100, v84
	v_exp_f32_e32 v119, v85
	v_exp_f32_e32 v101, v86
	v_exp_f32_e32 v120, v87
	v_exp_f32_e32 v121, v88
	v_exp_f32_e32 v122, v89
	v_exp_f32_e32 v90, v90
	v_exp_f32_e32 v91, v91
	v_exp_f32_e32 v92, v92
	v_exp_f32_e32 v118, v93
	v_exp_f32_e32 v93, v94
	v_exp_f32_e32 v94, v95
	v_exp_f32_e32 v95, v96
	v_exp_f32_e32 v96, v97
	v_exp_f32_e32 v186, v66
	v_exp_f32_e32 v187, v67
	v_exp_f32_e32 v188, v68
	v_exp_f32_e32 v189, v69
	v_exp_f32_e32 v97, v70
	v_exp_f32_e32 v124, v71
	v_exp_f32_e32 v125, v72
	v_exp_f32_e32 v128, v73
	v_exp_f32_e32 v123, v74
	v_exp_f32_e32 v126, v75
	v_exp_f32_e32 v127, v76
	v_exp_f32_e32 v129, v77
	v_exp_f32_e32 v74, v78
	v_exp_f32_e32 v75, v79
	v_exp_f32_e32 v76, v80
	v_exp_f32_e32 v77, v81
	v_cvt_pk_bf16_f32 v86, v98, v99
	v_cvt_pk_bf16_f32 v87, v100, v119
	v_cvt_pk_bf16_f32 v88, v101, v120
	v_cvt_pk_bf16_f32 v89, v121, v122
	v_cvt_pk_bf16_f32 v82, v90, v91
	v_cvt_pk_bf16_f32 v83, v92, v118
	v_cvt_pk_bf16_f32 v84, v93, v94
	v_cvt_pk_bf16_f32 v85, v95, v96
	v_cvt_pk_bf16_f32 v70, v186, v187
	v_cvt_pk_bf16_f32 v71, v188, v189
	v_cvt_pk_bf16_f32 v72, v97, v124
	v_cvt_pk_bf16_f32 v73, v125, v128
	v_cvt_pk_bf16_f32 v66, v123, v126
	v_cvt_pk_bf16_f32 v67, v127, v129
	v_cvt_pk_bf16_f32 v68, v74, v75
	v_cvt_pk_bf16_f32 v69, v76, v77
	s_barrier
	s_cmpk_lt_u32 s14, 0x100
	s_cbranch_scc0 .LBB0_89
	s_barrier
	s_branch .LBB0_89

; #define ATT_QK(S0_, S1_, kf_) do { \
;     _Pragma("unroll") for (int i_ = 0; i_ < 16; ++i_) { S0_[i_] = 0.f; S1_[i_] = 0.f; } \
;     _Pragma("unroll") for (int kk_ = 0; kk_ < 4; ++kk_) { \
;       S0_ = __builtin_amdgcn_mfma_f32_32x32x16_bf16(kf_[kk_], qf[0][kk_], S0_, 0, 0, 0); \
;       S1_ = __builtin_amdgcn_mfma_f32_32x32x16_bf16(kf_[kk_], qf[1][kk_], S1_, 0, 0, 0); } } while (0)
; #define ATT_PV(vf_, P0_, P1_) do { \
;     _Pragma("unroll") for (int c_ = 0; c_ < 2; ++c_) \
;     _Pragma("unroll") for (int db_ = 0; db_ < 2; ++db_) { \
;       O[db_][0] = __builtin_amdgcn_mfma_f32_32x32x16_bf16(vf_[db_ * 2 + c_], P0_[c_], O[db_][0], 0, 0, 0); \
;       O[db_][1] = __builtin_amdgcn_mfma_f32_32x32x16_bf16(vf_[db_ * 2 + c_], P1_[c_], O[db_][1], 0, 0, 0); } } while (0)
; __device__ __forceinline__ void exp_pack(f32x16& s, float& l, bf16x8& p0, bf16x8& p1) {
; #pragma unroll
;   for (int i = 0; i < 16; ++i) s[i] = __builtin_amdgcn_exp2f(s[i]);
;   const float a0 = (s[0] + s[1]) + (s[2] + s[3]), a1 = (s[4] + s[5]) + (s[6] + s[7]);
;   const float a2 = (s[8] + s[9]) + (s[10] + s[11]), a3 = (s[12] + s[13]) + (s[14] + s[15]);
;   l += (a0 + a1) + (a2 + a3);
;   p0 = pack8(s, 0); p1 = pack8(s, 8);
; }
; __device__ __forceinline__ void attn_item_fast(const u16* __restrict__ Qg, const u16* __restrict__ Kg, const u16* __restrict__ Vtg,
;                                                u16* __restrict__ Og, const int L, char* smem, const int tid) {
;     ...
;   for (int t = 0; t < NT; ++t) {
;     const int cur = (t & 1) * 8192;
;     const char* Kb = Ks + cur; const char* Vb = Vs + cur;
;     if (t + 1 < NT) {
;       const char* kb_ = (const char*)Kg + (size_t)(t + 1) * (64 * 256 * 2);
;       const char* vb_ = (const char*)Vtg + (size_t)(t + 1) * 128;
;       glds16(koff, kb_, ldsK + (unsigned)(cur ^ 8192)); glds16(voff, vb_, ldsV + (unsigned)(cur ^ 8192));
;     }
;     ld_kf<0>(kf, Kb, r32, hi, sw);
;     ATT_PV(vf, P0, P1);
;     ld_vf<0>(vf, Vb, r32, hi, sw);
;     ATT_QK(S0, S1, kf);
;     ld_kf<1>(kf, Kb, r32, hi, sw);
;     WBAR();
;     exp_pack(S0, l0, P0[0], P0[1]); exp_pack(S1, l1, P1[0], P1[1]);
;     WBAR();
;     ATT_PV(vf, P0, P1);
;     ld_vf<1>(vf, Vb, r32, hi, sw);
;     ATT_QK(S0, S1, kf);
;     asm volatile("s_waitcnt vmcnt(0) lgkmcnt(0)" ::: "memory");
;     WBAR();
;     exp_pack(S0, l0, P0[0], P0[1]); exp_pack(S1, l1, P1[0], P1[1]);
;     WBAR();
.LBB0_102:
	s_and_b32 s3, s53, 0x2000
	s_xor_b32 s13, s3, 0x2000
	s_add_i32 s15, s13, s49
	s_add_i32 s13, s13, s48
	s_mov_b32 s52, m0
	s_mov_b32 m0, s13
	s_nop 0
	global_load_lds_dwordx4 v168, s[10:11]
	s_mov_b32 m0, s52
	v_add_u32_e32 v82, s3, v170
	s_mov_b32 s13, m0
	s_mov_b32 m0, s15
	s_nop 0
	global_load_lds_dwordx4 v169, s[34:35]
	s_mov_b32 m0, s13
	v_add_u32_e32 v178, v82, v171
	ds_read_b128 v[146:149], v178
	s_waitcnt lgkmcnt(4)
	v_mfma_f32_32x32x16_bf16 v[50:65], v[142:145], v[74:77], v[50:65]
	v_add_u32_e32 v179, v82, v172
	ds_read_b128 v[150:153], v179
	v_add_u32_e32 v175, v82, v173
	v_add_u32_e32 v176, v82, v174
	ds_read_b128 v[154:157], v175
	ds_read_b128 v[158:161], v176
	v_mfma_f32_32x32x16_bf16 v[18:33], v[142:145], v[78:81], v[18:33]
	s_waitcnt lgkmcnt(6)
	v_mfma_f32_32x32x16_bf16 v[34:49], v[138:141], v[74:77], v[34:49]
	v_mfma_f32_32x32x16_bf16 v[2:17], v[138:141], v[78:81], v[2:17]
	s_waitcnt lgkmcnt(5)
	v_mfma_f32_32x32x16_bf16 v[50:65], v[134:137], v[70:73], v[50:65]
	v_mfma_f32_32x32x16_bf16 v[18:33], v[134:137], v[66:69], v[18:33]
	s_waitcnt lgkmcnt(4)
	v_mfma_f32_32x32x16_bf16 v[34:49], v[130:133], v[70:73], v[34:49]
	v_mfma_f32_32x32x16_bf16 v[2:17], v[130:133], v[66:69], v[2:17]
	ds_read_b128 v[142:145], v178 offset:16384
	ds_read_b128 v[134:137], v179 offset:16384
	ds_read_b128 v[138:141], v178 offset:20480
	ds_read_b128 v[130:133], v179 offset:20480
	s_waitcnt lgkmcnt(7)
	v_mfma_f32_32x32x16_bf16 v[66:81], v[146:149], v[126:129], 0
	v_mfma_f32_32x32x16_bf16 v[82:97], v[146:149], v[118:121], 0
	s_waitcnt lgkmcnt(6)
	v_mfma_f32_32x32x16_bf16 v[66:81], v[150:153], v[122:125], v[66:81]
	v_mfma_f32_32x32x16_bf16 v[82:97], v[150:153], v[114:117], v[82:97]
	s_waitcnt lgkmcnt(5)
	v_mfma_f32_32x32x16_bf16 v[66:81], v[154:157], v[110:113], v[66:81]
	v_mfma_f32_32x32x16_bf16 v[82:97], v[154:157], v[106:109], v[82:97]
	s_waitcnt lgkmcnt(4)
	v_mfma_f32_32x32x16_bf16 v[66:81], v[158:161], v[98:101], v[66:81]
	v_mfma_f32_32x32x16_bf16 v[82:97], v[158:161], v[102:105], v[82:97]
	ds_read_b128 v[146:149], v178 offset:4096
	ds_read_b128 v[150:153], v179 offset:4096
	ds_read_b128 v[154:157], v175 offset:4096
	ds_read_b128 v[158:161], v176 offset:4096
	s_barrier
	s_setprio 0
	s_nop 6
	v_exp_f32_e32 v82, v82
	v_exp_f32_e32 v178, v83
	v_exp_f32_e32 v84, v84
	v_exp_f32_e32 v180, v85
	v_exp_f32_e32 v83, v66
	v_exp_f32_e32 v179, v67
	v_exp_f32_e32 v85, v68
	v_exp_f32_e32 v181, v69
	v_exp_f32_e32 v86, v86
	v_exp_f32_e32 v182, v87
	v_exp_f32_e32 v88, v88
	v_exp_f32_e32 v184, v89
	v_exp_f32_e32 v87, v70
	v_exp_f32_e32 v183, v71
	v_exp_f32_e32 v89, v72
	v_exp_f32_e32 v185, v73
	v_exp_f32_e32 v90, v90
	v_exp_f32_e32 v186, v91
	v_exp_f32_e32 v92, v92
	v_exp_f32_e32 v188, v93
	v_exp_f32_e32 v91, v74
	v_exp_f32_e32 v187, v75
	v_exp_f32_e32 v93, v76
	v_exp_f32_e32 v189, v77
	v_exp_f32_e32 v94, v94
	v_exp_f32_e32 v206, v95
	v_exp_f32_e32 v96, v96
	v_exp_f32_e32 v208, v97
	v_exp_f32_e32 v95, v78
	v_exp_f32_e32 v207, v79
	v_exp_f32_e32 v97, v80
	v_exp_f32_e32 v209, v81
	v_add_f32_e32 v74, v82, v178
	v_add_f32_e32 v75, v83, v179
	v_add_f32_e32 v76, v84, v180
	v_add_f32_e32 v77, v85, v181
	v_add_f32_e32 v78, v88, v184
	v_add_f32_e32 v79, v89, v185
	v_add_f32_e32 v74, v74, v76
	v_add_f32_e32 v75, v75, v77
	v_add_f32_e32 v76, v86, v182
	v_add_f32_e32 v77, v87, v183
	v_add_f32_e32 v80, v92, v188
	v_add_f32_e32 v81, v93, v189
	v_add_f32_e32 v76, v76, v78
	v_add_f32_e32 v77, v77, v79
	v_add_f32_e32 v78, v90, v186
	v_add_f32_e32 v79, v91, v187
	v_add_f32_e32 v210, v96, v208
	v_add_f32_e32 v211, v97, v209
	v_add_f32_e32 v78, v78, v80
	v_add_f32_e32 v79, v79, v81
	v_add_f32_e32 v80, v94, v206
	v_add_f32_e32 v81, v95, v207
	v_add_f32_e32 v74, v74, v76
	v_add_f32_e32 v75, v75, v77
	v_add_f32_e32 v80, v80, v210
	v_add_f32_e32 v81, v81, v211
	v_cvt_pk_bf16_f32 v66, v82, v178
	v_cvt_pk_bf16_f32 v67, v84, v180
	v_cvt_pk_bf16_f32 v68, v86, v182
	v_cvt_pk_bf16_f32 v69, v88, v184
	v_cvt_pk_bf16_f32 v70, v90, v186
	s_nop 0
	v_add_f32_e32 v76, v78, v80
	v_add_f32_e32 v77, v79, v81
	v_cvt_pk_bf16_f32 v71, v92, v188
	v_cvt_pk_bf16_f32 v72, v94, v206
	v_cvt_pk_bf16_f32 v73, v96, v208
	v_cvt_pk_bf16_f32 v78, v91, v187
	v_cvt_pk_bf16_f32 v79, v93, v189
	s_nop 0
	v_add_f32_e32 v210, v74, v76
	v_add_f32_e32 v211, v75, v77
	v_cvt_pk_bf16_f32 v74, v83, v179
	v_cvt_pk_bf16_f32 v75, v85, v181
	v_cvt_pk_bf16_f32 v76, v87, v183
	v_cvt_pk_bf16_f32 v77, v89, v185
	v_cvt_pk_bf16_f32 v80, v95, v207
	v_cvt_pk_bf16_f32 v81, v97, v209
	s_barrier
	s_setprio 1
	s_waitcnt lgkmcnt(7)
	v_mfma_f32_32x32x16_bf16 v[50:65], v[142:145], v[66:69], v[50:65]
	v_mfma_f32_32x32x16_bf16 v[18:33], v[142:145], v[74:77], v[18:33]
	s_waitcnt lgkmcnt(5)
	v_mfma_f32_32x32x16_bf16 v[34:49], v[138:141], v[66:69], v[34:49]
	v_mfma_f32_32x32x16_bf16 v[2:17], v[138:141], v[74:77], v[2:17]
	v_mfma_f32_32x32x16_bf16 v[50:65], v[134:137], v[70:73], v[50:65]
	v_mfma_f32_32x32x16_bf16 v[18:33], v[134:137], v[78:81], v[18:33]
	s_waitcnt lgkmcnt(4)
	v_mfma_f32_32x32x16_bf16 v[34:49], v[130:133], v[70:73], v[34:49]
	v_mfma_f32_32x32x16_bf16 v[2:17], v[130:133], v[78:81], v[2:17]
	ds_read_b128 v[142:145], v175 offset:16384
	ds_read_b128 v[138:141], v175 offset:20480
	ds_read_b128 v[134:137], v176 offset:16384
	ds_read_b128 v[130:133], v176 offset:20480
	s_waitcnt vmcnt(0) lgkmcnt(0)
	s_waitcnt lgkmcnt(7)
	v_mfma_f32_32x32x16_bf16 v[66:81], v[146:149], v[126:129], 0
	v_mfma_f32_32x32x16_bf16 v[82:97], v[146:149], v[118:121], 0
	v_add_f32_e64 v146, v162, v210
	v_add_f32_e64 v147, v163, v211
	s_waitcnt lgkmcnt(6)
	v_mfma_f32_32x32x16_bf16 v[66:81], v[150:153], v[122:125], v[66:81]
	v_mfma_f32_32x32x16_bf16 v[82:97], v[150:153], v[114:117], v[82:97]
	s_waitcnt lgkmcnt(5)
	v_mfma_f32_32x32x16_bf16 v[66:81], v[154:157], v[110:113], v[66:81]
	v_mfma_f32_32x32x16_bf16 v[82:97], v[154:157], v[106:109], v[82:97]
	s_waitcnt lgkmcnt(4)
	v_mfma_f32_32x32x16_bf16 v[66:81], v[158:161], v[98:101], v[66:81]
	v_mfma_f32_32x32x16_bf16 v[82:97], v[158:161], v[102:105], v[82:97]
	s_barrier
; #define ATT_QK(S0_, S1_, kf_) do { \
;     _Pragma("unroll") for (int i_ = 0; i_ < 16; ++i_) { S0_[i_] = 0.f; S1_[i_] = 0.f; } \
;     _Pragma("unroll") for (int kk_ = 0; kk_ < 4; ++kk_) { \
;       S0_ = __builtin_amdgcn_mfma_f32_32x32x16_bf16(kf_[kk_], qf[0][kk_], S0_, 0, 0, 0); \
;       S1_ = __builtin_amdgcn_mfma_f32_32x32x16_bf16(kf_[kk_], qf[1][kk_], S1_, 0, 0, 0); } } while (0)
; #define ATT_PV(vf_, P0_, P1_) do { \
;     _Pragma("unroll") for (int c_ = 0; c_ < 2; ++c_) \
;     _Pragma("unroll") for (int db_ = 0; db_ < 2; ++db_) { \
;       O[db_][0] = __builtin_amdgcn_mfma_f32_32x32x16_bf16(vf_[db_ * 2 + c_], P0_[c_], O[db_][0], 0, 0, 0); \
;       O[db_][1] = __builtin_amdgcn_mfma_f32_32x32x16_bf16(vf_[db_ * 2 + c_], P1_[c_], O[db_][1], 0, 0, 0); } } while (0)
; #define WBAR() do { __builtin_amdgcn_sched_barrier(0); __builtin_amdgcn_s_barrier(); __builtin_amdgcn_sched_barrier(0); } while (0)
; __device__ __forceinline__ void attn_item_fast(const u16* __restrict__ Qg, const u16* __restrict__ Kg, const u16* __restrict__ Vtg,
;                                                u16* __restrict__ Og, const int L, char* smem, const int tid) {
;     ...
;     exp_pack(S0, l0, P0[0], P0[1]); exp_pack(S1, l1, P1[0], P1[1]);
;     WBAR();
;     ATT_PV(vf, P0, P1);
;     ld_vf<1>(vf, Vb, r32, hi, sw);
;     ATT_QK(S0, S1, kf);
;     asm volatile("s_waitcnt vmcnt(0) lgkmcnt(0)" ::: "memory");
;     WBAR();
;     exp_pack(S0, l0, P0[0], P0[1]); exp_pack(S1, l1, P1[0], P1[1]);
;     WBAR();
;   }
;   if (half == 0) WBAR();
	s_setprio 0
	s_nop 10
	v_exp_f32_e32 v82, v82
	v_exp_f32_e32 v148, v83
	v_exp_f32_e32 v84, v84
	v_exp_f32_e32 v150, v85
	v_exp_f32_e32 v83, v66
	v_exp_f32_e32 v149, v67
	v_exp_f32_e32 v85, v68
	v_exp_f32_e32 v151, v69
	v_exp_f32_e32 v86, v86
	v_exp_f32_e32 v152, v87
	v_exp_f32_e32 v88, v88
	v_exp_f32_e32 v154, v89
	v_exp_f32_e32 v87, v70
	v_exp_f32_e32 v153, v71
	v_exp_f32_e32 v89, v72
	v_exp_f32_e32 v155, v73
	v_exp_f32_e32 v90, v90
	v_exp_f32_e32 v156, v91
	v_exp_f32_e32 v92, v92
	v_exp_f32_e32 v158, v93
	v_exp_f32_e32 v91, v74
	v_exp_f32_e32 v157, v75
	v_exp_f32_e32 v93, v76
	v_exp_f32_e32 v159, v77
	v_exp_f32_e32 v94, v94
	v_exp_f32_e32 v160, v95
	v_exp_f32_e32 v96, v96
	v_exp_f32_e32 v178, v97
	v_exp_f32_e32 v95, v78
	v_exp_f32_e32 v161, v79
	v_exp_f32_e32 v97, v80
	v_exp_f32_e32 v179, v81
	v_add_f32_e32 v66, v82, v148
	v_add_f32_e32 v67, v83, v149
	v_add_f32_e32 v68, v84, v150
	v_add_f32_e32 v69, v85, v151
	v_add_f32_e32 v70, v88, v154
	v_add_f32_e32 v71, v89, v155
	v_add_f32_e32 v66, v66, v68
	v_add_f32_e32 v67, v67, v69
	v_add_f32_e32 v68, v86, v152
	v_add_f32_e32 v69, v87, v153
	v_add_f32_e32 v72, v92, v158
	v_add_f32_e32 v73, v93, v159
	v_add_f32_e32 v68, v68, v70
	v_add_f32_e32 v69, v69, v71
	v_add_f32_e32 v70, v90, v156
	v_add_f32_e32 v71, v91, v157
	v_add_f32_e32 v74, v96, v178
	v_add_f32_e32 v75, v97, v179
	v_add_f32_e32 v70, v70, v72
	v_add_f32_e32 v71, v71, v73
	v_add_f32_e32 v72, v94, v160
	v_add_f32_e32 v73, v95, v161
	v_add_f32_e32 v66, v66, v68
	v_add_f32_e32 v67, v67, v69
	v_add_f32_e32 v72, v72, v74
	v_add_f32_e32 v73, v73, v75
	v_cvt_pk_bf16_f32 v74, v82, v148
	v_cvt_pk_bf16_f32 v75, v84, v150
	v_cvt_pk_bf16_f32 v76, v86, v152
	v_cvt_pk_bf16_f32 v77, v88, v154
	v_cvt_pk_bf16_f32 v78, v83, v149
	s_nop 0
	v_add_f32_e32 v68, v70, v72
	v_add_f32_e32 v69, v71, v73
	v_cvt_pk_bf16_f32 v70, v90, v156
	v_cvt_pk_bf16_f32 v71, v92, v158
	v_cvt_pk_bf16_f32 v72, v94, v160
	v_cvt_pk_bf16_f32 v73, v96, v178
	v_cvt_pk_bf16_f32 v79, v85, v151
	s_nop 0
	v_add_f32_e32 v66, v66, v68
	v_add_f32_e32 v67, v67, v69
	v_cvt_pk_bf16_f32 v80, v87, v153
	v_cvt_pk_bf16_f32 v81, v89, v155
	v_cvt_pk_bf16_f32 v68, v95, v161
	v_cvt_pk_bf16_f32 v69, v97, v179
	s_nop 0
	v_add_f32_e32 v162, v146, v66
	v_add_f32_e32 v163, v147, v67
	v_cvt_pk_bf16_f32 v66, v91, v157
	v_cvt_pk_bf16_f32 v67, v93, v159
	s_barrier
	s_setprio 1
	s_addk_i32 s53, 0x2000
	s_add_u32 s10, s10, 0x8000
	s_addc_u32 s11, s11, 0
	s_add_u32 s34, s34, 0x80
	s_addc_u32 s35, s35, 0
	s_cmp_eq_u32 s53, 0x3e000
	s_cbranch_scc0 .LBB0_102
	s_setprio 0
	v_add_u32_e32 v175, v170, v171
	ds_read_b128 v[146:149], v175 offset:8192
	s_waitcnt lgkmcnt(4)
	v_mfma_f32_32x32x16_bf16 v[50:65], v[142:145], v[74:77], v[50:65]
	v_add_u32_e32 v176, v170, v172
	ds_read_b128 v[150:153], v176 offset:8192
	v_add_u32_e32 v205, v170, v173
	ds_read_b128 v[154:157], v205 offset:8192
	v_add_u32_e32 v226, v170, v174
	ds_read_b128 v[158:161], v226 offset:8192
	ds_read_b128 v[178:181], v175 offset:24576
	ds_read_b128 v[182:185], v176 offset:24576
	ds_read_b128 v[186:189], v175 offset:28672
	ds_read_b128 v[206:209], v176 offset:28672
	v_mfma_f32_32x32x16_bf16 v[18:33], v[142:145], v[78:81], v[18:33]
	ds_read_b128 v[210:213], v175 offset:12288
	ds_read_b128 v[214:217], v176 offset:12288
	ds_read_b128 v[218:221], v205 offset:12288
	ds_read_b128 v[222:225], v226 offset:12288
	s_waitcnt lgkmcnt(14)
	v_mfma_f32_32x32x16_bf16 v[34:49], v[138:141], v[74:77], v[34:49]
	v_mfma_f32_32x32x16_bf16 v[2:17], v[138:141], v[78:81], v[2:17]
	s_waitcnt lgkmcnt(13)
	v_mfma_f32_32x32x16_bf16 v[50:65], v[134:137], v[70:73], v[50:65]
	v_mfma_f32_32x32x16_bf16 v[18:33], v[134:137], v[66:69], v[18:33]
	s_waitcnt lgkmcnt(12)
	v_mfma_f32_32x32x16_bf16 v[34:49], v[130:133], v[70:73], v[34:49]
	v_mfma_f32_32x32x16_bf16 v[2:17], v[130:133], v[66:69], v[2:17]
	s_waitcnt lgkmcnt(11)
	v_mfma_f32_32x32x16_bf16 v[82:97], v[146:149], v[118:121], 0
	v_mfma_f32_32x32x16_bf16 v[66:81], v[146:149], v[126:129], 0
	s_waitcnt lgkmcnt(10)
	v_mfma_f32_32x32x16_bf16 v[82:97], v[150:153], v[114:117], v[82:97]
	v_mfma_f32_32x32x16_bf16 v[66:81], v[150:153], v[122:125], v[66:81]
	s_waitcnt lgkmcnt(9)
	v_mfma_f32_32x32x16_bf16 v[82:97], v[154:157], v[106:109], v[82:97]
	v_mfma_f32_32x32x16_bf16 v[66:81], v[154:157], v[110:113], v[66:81]
	s_waitcnt lgkmcnt(8)
	v_mfma_f32_32x32x16_bf16 v[82:97], v[158:161], v[102:105], v[82:97]
	v_mfma_f32_32x32x16_bf16 v[66:81], v[158:161], v[98:101], v[66:81]
	s_barrier
; #define ATT_QK(S0_, S1_, kf_) do { \
;     _Pragma("unroll") for (int i_ = 0; i_ < 16; ++i_) { S0_[i_] = 0.f; S1_[i_] = 0.f; } \
;     _Pragma("unroll") for (int kk_ = 0; kk_ < 4; ++kk_) { \
;       S0_ = __builtin_amdgcn_mfma_f32_32x32x16_bf16(kf_[kk_], qf[0][kk_], S0_, 0, 0, 0); \
;       S1_ = __builtin_amdgcn_mfma_f32_32x32x16_bf16(kf_[kk_], qf[1][kk_], S1_, 0, 0, 0); } } while (0)
; #define ATT_PV(vf_, P0_, P1_) do { \
;     _Pragma("unroll") for (int c_ = 0; c_ < 2; ++c_) \
;     _Pragma("unroll") for (int db_ = 0; db_ < 2; ++db_) { \
;       O[db_][0] = __builtin_amdgcn_mfma_f32_32x32x16_bf16(vf_[db_ * 2 + c_], P0_[c_], O[db_][0], 0, 0, 0); \
;       O[db_][1] = __builtin_amdgcn_mfma_f32_32x32x16_bf16(vf_[db_ * 2 + c_], P1_[c_], O[db_][1], 0, 0, 0); } } while (0)
; #define WBAR() do { __builtin_amdgcn_sched_barrier(0); __builtin_amdgcn_s_barrier(); __builtin_amdgcn_sched_barrier(0); } while (0)
; __device__ __forceinline__ void attn_item_fast(const u16* __restrict__ Qg, const u16* __restrict__ Kg, const u16* __restrict__ Vtg,
;                                                u16* __restrict__ Og, const int L, char* smem, const int tid) {
;     ...
;     ld_kf<0>(kf, Kb, r32, hi, sw);
;     ATT_PV(vf, P0, P1);
;     ld_vf<0>(vf, Vb, r32, hi, sw);
;     ATT_QK(S0, S1, kf);
;     ld_kf<1>(kf, Kb, r32, hi, sw);
;     WBAR();
;     exp_pack(S0, l0, P0[0], P0[1]); exp_pack(S1, l1, P1[0], P1[1]);
;     WBAR();
;     ATT_PV(vf, P0, P1);
;     ld_vf<1>(vf, Vb, r32, hi, sw);
;     ATT_QK(S0, S1, kf);
;     asm volatile("s_waitcnt vmcnt(0) lgkmcnt(0)" ::: "memory");
;     WBAR();
;     exp_pack(S0, l0, P0[0], P0[1]); exp_pack(S1, l1, P1[0], P1[1]);
;     WBAR();
;   }
;   if (half == 0) WBAR();
	s_nop 9
	v_exp_f32_e32 v138, v82
	v_exp_f32_e32 v144, v83
	v_exp_f32_e32 v132, v84
	v_exp_f32_e32 v139, v85
	v_exp_f32_e32 v133, v86
	v_exp_f32_e32 v140, v87
	v_exp_f32_e32 v141, v88
	v_exp_f32_e32 v145, v89
	v_exp_f32_e32 v134, v90
	v_exp_f32_e32 v142, v91
	v_exp_f32_e32 v130, v92
	v_exp_f32_e32 v135, v93
	v_exp_f32_e32 v131, v94
	v_exp_f32_e32 v136, v95
	v_exp_f32_e32 v137, v96
	v_exp_f32_e32 v143, v97
	v_exp_f32_e32 v146, v66
	v_exp_f32_e32 v147, v67
	v_exp_f32_e32 v148, v68
	v_exp_f32_e32 v151, v69
	v_exp_f32_e32 v149, v70
	v_exp_f32_e32 v152, v71
	v_exp_f32_e32 v153, v72
	v_exp_f32_e32 v157, v73
	v_exp_f32_e32 v150, v74
	v_exp_f32_e32 v154, v75
	v_exp_f32_e32 v155, v76
	v_exp_f32_e32 v158, v77
	v_exp_f32_e32 v156, v78
	v_exp_f32_e32 v159, v79
	v_exp_f32_e32 v160, v80
	v_exp_f32_e32 v161, v81
	v_cvt_pk_bf16_f32 v82, v138, v144
	v_cvt_pk_bf16_f32 v83, v132, v139
	v_cvt_pk_bf16_f32 v84, v133, v140
	v_cvt_pk_bf16_f32 v85, v141, v145
	v_cvt_pk_bf16_f32 v86, v134, v142
	v_cvt_pk_bf16_f32 v87, v130, v135
	v_cvt_pk_bf16_f32 v88, v131, v136
	v_cvt_pk_bf16_f32 v89, v137, v143
	v_cvt_pk_bf16_f32 v66, v146, v147
	v_cvt_pk_bf16_f32 v67, v148, v151
	v_cvt_pk_bf16_f32 v68, v149, v152
	v_cvt_pk_bf16_f32 v69, v153, v157
	v_cvt_pk_bf16_f32 v70, v150, v154
	v_cvt_pk_bf16_f32 v71, v155, v158
	v_cvt_pk_bf16_f32 v72, v156, v159
	v_cvt_pk_bf16_f32 v73, v160, v161
	s_barrier
	s_waitcnt lgkmcnt(7)
	v_mfma_f32_32x32x16_bf16 v[50:65], v[178:181], v[82:85], v[50:65]
	v_mfma_f32_32x32x16_bf16 v[18:33], v[178:181], v[66:69], v[18:33]
	s_waitcnt lgkmcnt(5)
	v_mfma_f32_32x32x16_bf16 v[34:49], v[186:189], v[82:85], v[34:49]
	v_mfma_f32_32x32x16_bf16 v[2:17], v[186:189], v[66:69], v[2:17]
	v_mfma_f32_32x32x16_bf16 v[50:65], v[182:185], v[86:89], v[50:65]
	v_mfma_f32_32x32x16_bf16 v[18:33], v[182:185], v[70:73], v[18:33]
	s_waitcnt lgkmcnt(4)
	v_mfma_f32_32x32x16_bf16 v[34:49], v[206:209], v[86:89], v[34:49]
	v_mfma_f32_32x32x16_bf16 v[2:17], v[206:209], v[70:73], v[2:17]
	s_waitcnt lgkmcnt(3)
	v_mfma_f32_32x32x16_bf16 v[82:97], v[210:213], v[118:121], 0
	v_mfma_f32_32x32x16_bf16 v[66:81], v[210:213], v[126:129], 0
	s_waitcnt lgkmcnt(2)
	v_mfma_f32_32x32x16_bf16 v[82:97], v[214:217], v[114:117], v[82:97]
	v_mfma_f32_32x32x16_bf16 v[66:81], v[214:217], v[122:125], v[66:81]
	s_waitcnt lgkmcnt(1)
	v_mfma_f32_32x32x16_bf16 v[82:97], v[218:221], v[106:109], v[82:97]
	v_mfma_f32_32x32x16_bf16 v[66:81], v[218:221], v[110:113], v[66:81]
	s_waitcnt lgkmcnt(0)
	v_mfma_f32_32x32x16_bf16 v[82:97], v[222:225], v[102:105], v[82:97]
	ds_read_b128 v[114:117], v205 offset:24576
	ds_read_b128 v[110:113], v205 offset:28672
	ds_read_b128 v[106:109], v226 offset:24576
	ds_read_b128 v[102:105], v226 offset:28672
	s_waitcnt vmcnt(0) lgkmcnt(0)
	v_mfma_f32_32x32x16_bf16 v[66:81], v[222:225], v[98:101], v[66:81]
	s_barrier
	s_nop 5
	v_exp_f32_e32 v98, v82
	v_exp_f32_e32 v99, v83
	v_exp_f32_e32 v100, v84
	v_exp_f32_e32 v119, v85
	v_exp_f32_e32 v101, v86
	v_exp_f32_e32 v120, v87
	v_exp_f32_e32 v121, v88
	v_exp_f32_e32 v122, v89
	v_exp_f32_e32 v90, v90
	v_exp_f32_e32 v91, v91
	v_exp_f32_e32 v92, v92
	v_exp_f32_e32 v118, v93
	v_exp_f32_e32 v93, v94
	v_exp_f32_e32 v94, v95
	v_exp_f32_e32 v95, v96
	v_exp_f32_e32 v96, v97
	v_exp_f32_e32 v175, v66
	v_exp_f32_e32 v176, v67
	v_exp_f32_e32 v178, v68
	v_exp_f32_e32 v179, v69
	v_exp_f32_e32 v97, v70
	v_exp_f32_e32 v124, v71
	v_exp_f32_e32 v125, v72
	v_exp_f32_e32 v128, v73
	v_exp_f32_e32 v123, v74
	v_exp_f32_e32 v126, v75
	v_exp_f32_e32 v127, v76
	v_exp_f32_e32 v129, v77
	v_exp_f32_e32 v74, v78
	v_exp_f32_e32 v75, v79
	v_exp_f32_e32 v76, v80
	v_exp_f32_e32 v77, v81
	v_cvt_pk_bf16_f32 v86, v98, v99
	v_cvt_pk_bf16_f32 v87, v100, v119
	v_cvt_pk_bf16_f32 v88, v101, v120
	v_cvt_pk_bf16_f32 v89, v121, v122
	v_cvt_pk_bf16_f32 v82, v90, v91
	v_cvt_pk_bf16_f32 v83, v92, v118
	v_cvt_pk_bf16_f32 v84, v93, v94
	v_cvt_pk_bf16_f32 v85, v95, v96
	v_cvt_pk_bf16_f32 v70, v175, v176
	v_cvt_pk_bf16_f32 v71, v178, v179
	v_cvt_pk_bf16_f32 v72, v97, v124
	v_cvt_pk_bf16_f32 v73, v125, v128
	v_cvt_pk_bf16_f32 v66, v123, v126
	v_cvt_pk_bf16_f32 v67, v127, v129
	v_cvt_pk_bf16_f32 v68, v74, v75
	v_cvt_pk_bf16_f32 v69, v76, v77
	s_barrier
	s_cmpk_lt_u32 s14, 0x100
	s_cbranch_scc0 .LBB0_98
	s_barrier
	s_branch .LBB0_98
